# f32 output stores of the last down-projection widened with v_permlane32_swap: 64 contiguous bytes per row per store instruction
# speedup vs baseline: 1.0066x; 1.0066x over previous
; __device__ __forceinline__ unsigned xb_ld(unsigned* p)              { return __hip_atomic_load(p, __ATOMIC_RELAXED, __HIP_MEMORY_SCOPE_AGENT); }
;     __host__ __device__ bool next(int i, Unit& u) const {
;         if (rev_n) { i = rev_n - 1 - i; if (i < 0) return false; }
;         const long L = (long)i * G + c; if (L >= nwg) return false;
;         int wgid = (int)L; { const int q = nwg / NXCD, r = nwg % NXCD, xcd = wgid % NXCD, off = wgid / NXCD; wgid = (xcd < r ? xcd * (q + 1) : r * (q + 1) + (xcd - r) * q) + off; }
; __device__ __forceinline__ void xcd_barrier_complete(unsigned* bar, unsigned x, unsigned& nloc, unsigned& nx) {
;     const unsigned G = gridDim.x * gridDim.y * gridDim.z;
;     unsigned sum, cnt, mine, sp = 0u;
;     for (;;) {
;         sum = 0u; cnt = 0u; mine = 0u;
; #pragma unroll
;         for (unsigned j = 0; j < 16; ++j) { const unsigned c = xb_ld(&bar[XB_XCNT(j)]); sum += c; cnt += (c > 0u) ? 1u : 0u; mine = (j == x) ? c : mine; }
;         if (sum == G) break;
;         __builtin_amdgcn_s_sleep(1);
;         if ((++sp & 255u) == 0u) { if (xb_ld(&bar[XB_TMO])) break; if (sp > XB_SPIN_CAP) { atomicAdd(&bar[XB_TMO], 1u); break; } }
;     }
;     nloc = mine > 0u ? mine : 1u; nx = cnt > 0u ? cnt : 1u;
.LBB0_5:
	s_or_b64 exec, exec, s[4:5]
	s_cmpk_lt_i32 s2, 0x100
	s_cselect_b64 s[4:5], -1, 0
	v_writelane_b32 v253, s4, 8
	s_cmpk_lt_i32 s2, 0x800
	v_lshrrev_b32_e32 v1, 20, v0
	v_writelane_b32 v253, s5, 9
	s_cselect_b64 s[4:5], -1, 0
	v_writelane_b32 v253, s4, 10
	s_ashr_i32 s3, s2, 31
	s_add_i32 s13, 0, 0x20400
	v_writelane_b32 v253, s5, 11
	s_lshr_b32 s4, s3, 29
	s_add_i32 s4, s2, s4
	s_ashr_i32 s5, s4, 3
	s_and_b32 s4, s4, -8
	s_sub_i32 s6, s2, s4
	s_lshl_b32 s7, s6, 8
	s_cmpk_lt_i32 s2, 0xb00
	s_cselect_b64 s[14:15], -1, 0
	v_writelane_b32 v253, s14, 12
	s_cmpk_lt_i32 s2, 0x200
	v_lshrrev_b32_e32 v0, 10, v0
	v_writelane_b32 v253, s15, 13
	s_cselect_b64 s[14:15], -1, 0
	s_sub_i32 s4, 0x1ff, s2
	v_writelane_b32 v253, s14, 14
	s_cmpk_lt_i32 s2, 0x400
	v_or_b32_e32 v0, v0, v1
	v_writelane_b32 v253, s15, 15
	s_cselect_b64 s[14:15], -1, 0
	v_writelane_b32 v253, s14, 16
	s_lshl_b32 s10, s6, 7
	v_mbcnt_lo_u32_b32 v2, -1, 0
	v_writelane_b32 v253, s15, 17
	s_lshl_b32 s14, s2, 3
	v_writelane_b32 v253, s14, 18
	s_lshl_b32 s14, s2, 9
	v_writelane_b32 v253, s14, 19
	s_add_u32 s14, s0, 0x80200
	s_addc_u32 s15, s1, 0
	s_add_u32 s60, s0, 0x80400
	s_addc_u32 s61, s1, 0
	s_add_u32 s64, s0, 0x80500
	s_addc_u32 s65, s1, 0
	s_add_u32 s70, s0, 0x80600
	s_addc_u32 s71, s1, 0
	s_add_u32 s72, s0, 0x80700
	s_addc_u32 s73, s1, 0
	s_add_u32 s74, s0, 0x80800
	s_addc_u32 s75, s1, 0
	s_add_u32 s76, s0, 0x80900
	s_addc_u32 s77, s1, 0
	s_add_u32 s94, s0, 0x80a00
	s_addc_u32 s95, s1, 0
	s_add_u32 s96, s0, 0x80b00
	s_addc_u32 s97, s1, 0
	s_add_u32 s98, s0, 0x80c00
	v_writelane_b32 v253, s14, 20
	s_addc_u32 s99, s1, 0
	v_writelane_b32 v197, s94, 0
	v_writelane_b32 v253, s15, 21
	s_add_u32 s14, s0, 0x80d00
	s_addc_u32 s15, s1, 0
	v_writelane_b32 v253, s14, 22
	v_writelane_b32 v197, s95, 1
	v_writelane_b32 v197, s96, 2
	v_writelane_b32 v253, s15, 23
	s_add_u32 s14, s0, 0x80e00
	s_addc_u32 s15, s1, 0
	v_writelane_b32 v253, s14, 24
	v_mbcnt_hi_u32_b32 v234, -1, v2
	s_mov_b32 s24, 0xfffe0000
	v_writelane_b32 v253, s15, 25
	s_add_u32 s14, s0, 0x80f00
	s_addc_u32 s15, s1, 0
	v_writelane_b32 v253, s14, 26
	v_writelane_b32 v197, s97, 3
	v_lshl_add_u32 v231, v230, 2, s13
	v_writelane_b32 v253, s15, 27
	s_add_u32 s14, s0, 0x81000
	s_addc_u32 s15, s1, 0
	v_writelane_b32 v253, s14, 28
	v_mov_b32_e32 v1, 0
	v_mov_b32_e32 v232, 0x358637bd
	v_writelane_b32 v253, s15, 29
	s_add_u32 s14, s0, 0x81100
	s_addc_u32 s15, s1, 0
	v_writelane_b32 v253, s14, 30
	v_mov_b32_e32 v244, 1
	v_and_b32_e32 v235, 64, v234
	v_writelane_b32 v253, s15, 31
	s_add_u32 s14, s0, 0x81200
	s_addc_u32 s15, s1, 0
	v_writelane_b32 v253, s14, 32
	v_add_u32_e32 v245, -1, v234
	v_add_u32_e32 v233, -2, v234
	v_writelane_b32 v253, s15, 33
	s_add_u32 s14, s0, 0x81300
	s_addc_u32 s15, s1, 0
	v_writelane_b32 v253, s14, 34
	s_cmp_eq_u32 s11, 15
	v_add_u32_e32 v238, -4, v234
	v_writelane_b32 v253, s15, 35
	s_cselect_b64 s[14:15], -1, 0
	v_writelane_b32 v253, s14, 36
	s_cmp_eq_u32 s11, 14
	v_add_u32_e32 v239, -8, v234
	v_writelane_b32 v253, s15, 37
	s_cselect_b64 s[14:15], -1, 0
	v_writelane_b32 v253, s14, 38
	s_cmp_eq_u32 s11, 13
	v_add_u32_e32 v240, -16, v234
	v_writelane_b32 v253, s15, 39
	s_cselect_b64 s[14:15], -1, 0
	v_writelane_b32 v253, s14, 40
	s_cmp_eq_u32 s11, 12
	v_subrev_u32_e32 v196, 32, v234
	v_writelane_b32 v253, s15, 41
	s_cselect_b64 s[14:15], -1, 0
	v_writelane_b32 v253, s14, 42
	s_cmp_eq_u32 s11, 11
	v_mov_b32_e32 v242, 0xff800000
	v_writelane_b32 v253, s15, 43
	s_cselect_b64 s[14:15], -1, 0
	v_writelane_b32 v253, s14, 44
	s_cmp_eq_u32 s11, 10
	v_mov_b32_e32 v243, 0x7f800000
	v_writelane_b32 v253, s15, 45
	s_cselect_b64 s[14:15], -1, 0
	v_writelane_b32 v253, s14, 46
	s_cmp_eq_u32 s11, 9
	v_writelane_b32 v253, s15, 47
	s_cselect_b64 s[14:15], -1, 0
	v_writelane_b32 v253, s14, 48
	s_cmp_eq_u32 s11, 8
	v_writelane_b32 v253, s15, 49
	s_cselect_b64 s[14:15], -1, 0
	v_writelane_b32 v253, s14, 50
	s_cmp_eq_u32 s11, 7
	s_mov_b32 s67, 0x42200000
	v_writelane_b32 v253, s15, 51
	s_cselect_b64 s[14:15], -1, 0
	v_writelane_b32 v253, s14, 52
	s_cmp_eq_u32 s11, 6
	s_movk_i32 s55, 0x4000
	v_writelane_b32 v253, s15, 53
	s_cselect_b64 s[14:15], -1, 0
	v_writelane_b32 v253, s14, 54
	s_cmp_eq_u32 s11, 5
	s_mov_b32 s35, 0x3a800000
	v_writelane_b32 v253, s15, 55
	s_cselect_b64 s[14:15], -1, 0
	v_writelane_b32 v253, s14, 56
	s_cmp_eq_u32 s11, 4
	s_mov_b32 s19, 0xbfb8aa3b
	v_writelane_b32 v253, s15, 57
	s_cselect_b64 s[14:15], -1, 0
	v_writelane_b32 v253, s14, 58
	s_cmp_eq_u32 s11, 3
	s_mov_b32 s23, 0x40000
	v_writelane_b32 v253, s15, 59
	s_cselect_b64 s[14:15], -1, 0
	v_writelane_b32 v253, s14, 60
	s_cmp_eq_u32 s11, 2
	s_movk_i32 s86, 0x1600
	v_writelane_b32 v253, s15, 61
	s_cselect_b64 s[14:15], -1, 0
	v_writelane_b32 v253, s14, 62
	s_cmp_eq_u32 s11, 1
	s_movk_i32 s87, 0x4040
	v_writelane_b32 v253, s15, 63
	s_cselect_b64 s[14:15], -1, 0
	v_writelane_b32 v254, s14, 0
	s_cmp_eq_u32 s11, 0
	s_mov_b32 s88, 0
	v_writelane_b32 v254, s15, 1
	s_cselect_b64 s[14:15], -1, 0
	s_lshl_b32 s11, s12, 2
	s_add_u32 s8, s8, s11
	v_writelane_b32 v254, s14, 2
	s_addc_u32 s9, s9, 0
	s_mov_b64 s[36:37], 0x20000
	v_writelane_b32 v254, s15, 3
	s_add_u32 s14, s8, 0x1400
	s_addc_u32 s15, s9, 0
	v_writelane_b32 v254, s14, 4
	s_add_u32 s8, s8, 0x2400
	s_addc_u32 s9, s9, 0
	v_writelane_b32 v254, s15, 5
	v_writelane_b32 v254, s8, 6
	s_mov_b64 s[62:63], 0x40000
	s_mov_b32 s25, -1
	v_writelane_b32 v254, s9, 7
	s_add_u32 s8, s0, 0x83400
	s_addc_u32 s9, s1, 0
	v_writelane_b32 v254, s8, 8
	s_add_u32 s0, s0, 0x83500
	s_addc_u32 s1, s1, 0
	v_writelane_b32 v254, s9, 9
	v_writelane_b32 v254, s0, 10
	v_readlane_b32 s8, v253, 2
	v_readlane_b32 s9, v253, 3
	v_writelane_b32 v254, s1, 11
	v_readlane_b32 s0, v253, 0
	v_readlane_b32 s1, v253, 1
	s_mul_i32 s0, s1, s0
	s_load_dword s1, s[8:9], 0xa0
	s_cmp_lt_i32 s6, 0
	s_mov_b64 s[30:31], 0x80
	s_mov_b64 s[16:17], 0x400
	s_mov_b64 s[40:41], 0x200
	s_waitcnt lgkmcnt(0)
;     __host__ __device__ bool next(int i, Unit& u) const {
;         if (rev_n) { i = rev_n - 1 - i; if (i < 0) return false; }
;         const long L = (long)i * G + c; if (L >= nwg) return false;
;         int wgid = (int)L; { const int q = nwg / NXCD, r = nwg % NXCD, xcd = wgid % NXCD, off = wgid / NXCD; wgid = (xcd < r ? xcd * (q + 1) : r * (q + 1) + (xcd - r) * q) + off; }
;         const int nig = WGM * nN, gid = wgid / nig, fm = gid * WGM, gsz = (nM % WGM == 0) ? WGM : ((nM - fm) < WGM ? (nM - fm) : WGM);
;         u.pm = fm + ((wgid % nig) % gsz); u.pn = (wgid % nig) / gsz; return true;
	s_mul_i32 s0, s0, s1
	v_writelane_b32 v254, s0, 12
	s_movk_i32 s0, 0x3ff
	v_and_or_b32 v0, v0, s0, v230
	s_mul_i32 s0, s6, 0x101
	s_cselect_b32 s0, s0, s7
	s_mul_i32 s1, s6, 0x81
	s_movk_i32 s7, 0x161
	s_cselect_b32 s1, s1, s10
	s_cselect_b32 s7, s7, 0x160
	s_add_i32 s0, s0, s5
	s_ashr_i32 s8, s0, 31
	s_lshr_b32 s8, s8, 25
	s_add_i32 s8, s0, s8
	s_and_b32 s9, s8, 0xff80
	s_sub_i32 s0, s0, s9
	s_bfe_i32 s9, s0, 0x80000
	s_bfe_u32 s9, s9, 0x3000c
	s_mul_i32 s6, s6, s7
	s_add_i32 s9, s0, s9
	s_add_i32 s6, s6, s5
	s_and_b32 s10, s9, 0xf8
	s_mul_hi_i32 s7, s6, 0x2e8ba2e9
	s_sub_i32 s0, s0, s10
	s_lshr_b32 s10, s7, 31
	s_ashr_i32 s7, s7, 5
	s_add_i32 s7, s7, s10
	s_mul_i32 s10, s7, 0xb0
	s_sub_i32 s6, s6, s10
	s_add_i32 s1, s1, s5
	s_bfe_u32 s10, s6, 0x3001c
	s_ashr_i32 s5, s1, 31
	s_add_i32 s10, s6, s10
	s_lshr_b32 s5, s5, 26
	s_and_b32 s11, s10, 0xfff8
	s_add_i32 s5, s1, s5
	s_sub_i32 s6, s6, s11
	s_and_b32 s11, s5, 0xffc0
	s_sub_i32 s1, s1, s11
	s_bfe_i32 s11, s1, 0x80000
	s_bfe_u32 s11, s11, 0x3000c
	s_add_i32 s11, s1, s11
	s_and_b32 s12, s11, 0xf8
	s_sub_i32 s12, s1, s12
	s_ashr_i32 s1, s8, 7
	s_lshl_b32 s1, s1, 3
	s_sext_i32_i8 s0, s0
	s_add_i32 s14, s1, s0
	s_lshl_b32 s0, s7, 3
	s_sext_i32_i16 s1, s10
	s_sext_i32_i16 s6, s6
	s_add_i32 s6, s0, s6
	s_ashr_i32 s0, s1, 3
	v_writelane_b32 v254, s0, 13
	s_lshr_b32 s0, s1, 3
	s_bfe_i64 s[0:1], s[0:1], 0x100000
	s_lshl_b64 s[0:1], s[0:1], 19
	v_writelane_b32 v254, s0, 14
	s_bfe_i32 s8, s9, 0x80000
	s_sext_i32_i16 s8, s8
	v_writelane_b32 v254, s1, 15
	s_ashr_i32 s0, s5, 6
	s_bfe_i32 s1, s11, 0x80000
	s_lshl_b32 s0, s0, 3
	s_sext_i32_i16 s5, s1
	s_sext_i32_i8 s1, s12
	s_add_i32 s10, s0, s1
	s_ashr_i32 s0, s8, 3
	v_writelane_b32 v254, s0, 16
	s_lshr_b32 s0, s8, 3
	s_bfe_i64 s[0:1], s[0:1], 0x100000
	s_lshl_b64 s[0:1], s[0:1], 19
	v_writelane_b32 v254, s0, 17
	s_ashr_i32 s7, s6, 31
	s_ashr_i32 s15, s14, 31
	v_writelane_b32 v254, s1, 18
	s_ashr_i32 s0, s5, 3
	v_writelane_b32 v254, s0, 19
	s_lshr_b32 s0, s5, 3
	s_bfe_i64 s[0:1], s[0:1], 0x100000
	s_lshl_b64 s[0:1], s[0:1], 19
	v_writelane_b32 v254, s0, 20
	s_ashr_i32 s11, s10, 31
	s_mov_b64 s[12:13], 0x60000
	v_writelane_b32 v254, s1, 21
	s_ashr_i32 s0, s4, 31
	v_writelane_b32 v254, s0, 22
	s_abs_i32 s0, s4
	v_writelane_b32 v254, s0, 23
	s_movk_i32 s0, 0x100
	v_cmp_gt_u32_e64 s[0:1], s0, v230
	s_mov_b32 s28, 0x3e6d3388
	s_mov_b32 s22, 0xbf38aa3b
	v_writelane_b32 v254, s0, 24
	s_mov_b32 s54, 0xbf3a00e3
	s_mov_b32 s66, 0x3f07dc22
	v_writelane_b32 v254, s1, 25
	s_lshl_b32 s0, s2, 5
	v_writelane_b32 v254, s0, 26
	s_lshl_b32 s0, s2, 12
	v_writelane_b32 v254, s0, 27
	s_add_i32 s0, 0, 0x17050
	v_writelane_b32 v254, s0, 28
	s_add_i32 s0, 0, 0x17060
	v_writelane_b32 v254, s0, 29
	s_add_i32 s0, 0, 0x17070
	v_writelane_b32 v254, s0, 30
	s_add_i32 s0, 0, 0x17080
	v_writelane_b32 v254, s0, 31
	s_add_i32 s0, 0, 0x17090
	v_writelane_b32 v254, s0, 32
	s_add_i32 s0, 0, 0x170a0
	v_writelane_b32 v254, s0, 33
	s_add_i32 s0, 0, 0x170b0
	v_writelane_b32 v254, s0, 34
	s_add_i32 s0, 0, 0x17180
	v_writelane_b32 v254, s0, 35
	s_add_i32 s0, 0, 0x20140
	v_writelane_b32 v254, s0, 36
	s_add_i32 s0, 0, 0x20144
	v_writelane_b32 v254, s0, 37
	v_cmp_eq_u32_e64 s[0:1], 0, v0
	s_mov_b32 s68, 0x3f35f0e3
	s_mov_b32 s26, 0xbe11a98e
	v_writelane_b32 v254, s0, 38
	s_mov_b32 s34, 0x3e027906
	v_writelane_b32 v197, s98, 4
	v_writelane_b32 v254, s1, 39
	s_mov_b32 s0, s6
	v_writelane_b32 v254, s0, 40
	v_writelane_b32 v197, s99, 5
	s_nop 0
	v_writelane_b32 v254, s1, 41
	s_lshl_b64 s[0:1], s[6:7], 19
	v_writelane_b32 v254, s0, 42
	s_nop 1
	v_writelane_b32 v254, s1, 43
	s_mov_b32 s0, s14
	v_writelane_b32 v254, s0, 44
	s_nop 1
	v_writelane_b32 v254, s1, 45
	s_lshl_b64 s[0:1], s[14:15], 19
	v_writelane_b32 v254, s0, 46
	s_nop 1
	v_writelane_b32 v254, s1, 47
	s_mov_b32 s0, s10
	v_writelane_b32 v254, s0, 48
	s_nop 1
	v_writelane_b32 v254, s1, 49
	s_lshl_b64 s[0:1], s[10:11], 19
	v_writelane_b32 v254, s0, 50
	s_nop 1
	v_writelane_b32 v254, s1, 51
	v_writelane_b32 v254, s60, 52
	s_nop 1
	v_writelane_b32 v254, s61, 53
	v_writelane_b32 v254, s64, 54
	s_nop 1
	v_writelane_b32 v254, s65, 55
	v_writelane_b32 v254, s70, 56
	s_nop 1
	v_writelane_b32 v254, s71, 57
	v_writelane_b32 v254, s72, 58
	s_nop 1
	v_writelane_b32 v254, s73, 59
	v_writelane_b32 v254, s74, 60
	s_nop 1
	v_writelane_b32 v254, s75, 61
	v_writelane_b32 v254, s76, 62
	s_nop 1
	v_writelane_b32 v254, s77, 63
	s_branch .LBB0_10

; template <class Epi, class Sched, bool ALIGN_EPI = false, bool SP2 = false>
; __device__ __forceinline__ void gemm_phase(PG8_LAS unsigned char* lds, const Gemm g, const Sched& S, const Epi& E) {
;     ...
;     for (int i = 0; i < 2; ++i) { int R, C; stage_rc(tid * 16 + i * 8192, R, C); const int Rb = Epi::PERM ? ((R & ~31) + perm32(R & 31)) : R;
;         voffA[i] = (unsigned)(R * K + C) * 2u; voffB[i] = (unsigned)(Rb * K + C) * 2u; }
;     const size_t kstep = (size_t)(BK * 2);
;     const size_t hstep = (size_t)HALF * K * 2;
;     const size_t tstep = 2 * hstep;
;     const unsigned ldsw = (unsigned)wid * 1024u;
;     const int aoff = lds_byte(wr * 64 + fr, fq * 8), boff = lds_byte(wc * 32 + fr, fq * 8);
;     ...
;     Unit cur, nxt; int ui = 0;
;     if (!S.next(0, cur)) return;
;     typedef unsigned long long u64x2_t __attribute__((ext_vector_type(2)));
;     f32x4 acc[2][2][4][2];
;     int rs_pm = -1, rs_tog = 0;
; #pragma unroll
;     for (int a = 0; a < 2; ++a)
; #pragma unroll
;         for (int b = 0; b < 2; ++b)
; #pragma unroll
;             for (int m = 0; m < 4; ++m)
; #pragma unroll
;                 for (int n = 0; n < 2; ++n) { unsigned long long lo_, hi_; asm volatile("v_mov_b64 %0, 0\n\tv_mov_b64 %1, 0" : "=v"(lo_), "=v"(hi_)); acc[a][b][m][n] = __builtin_bit_cast(f32x4, (u64x2_t){lo_, hi_}); }
;     bf16x8 At[4][2], B0[2][2], B1[2][2];
;     const char* cA = (const char*)g.A + (size_t)cur.pm * tstep; const char* cB = (const char*)g.Bt + (size_t)cur.pn * tstep;
;     S.a_ready(cur);
;     if constexpr (SP2) {
;         PG8_STAGE(PG8_SB(0, 0), cB, voffB); PG8_STAGE(PG8_SB(0, 1), cB + hstep, voffB); PG8_STAGE(PG8_SA(0, 0), cA, voffA); PG8_STAGE(PG8_SA(0, 1), cA + hstep, voffA);
;         if (wr == 1) PG8_BAR;
;         PG8_WAIT_V(2); PG8_BAR;
;         PG8_STAGE(PG8_SB(1, 0), cB + kstep, voffB); PG8_STAGE(PG8_SA(1, 0), cA + kstep, voffA); PG8_STAGE(PG8_SB(1, 1), cB + hstep + kstep, voffB);
;         PG8_WAIT_V(6); PG8_BAR;
;     } else {
;         PG8_STAGE(PG8_SB(0, 0), cB, voffB); PG8_STAGE(PG8_SA(0, 0), cA, voffA); PG8_STAGE(PG8_SB(0, 1), cB + hstep, voffB); PG8_STAGE(PG8_SA(0, 1), cA + hstep, voffA);
;         if (wr == 1) PG8_BAR;
;         PG8_WAIT_V(4); PG8_BAR;
;         PG8_STAGE(PG8_SB(1, 0), cB + kstep, voffB); PG8_STAGE(PG8_SA(1, 0), cA + kstep, voffA); PG8_STAGE(PG8_SB(1, 1), cB + hstep + kstep, voffB);
;         PG8_WAIT_V(6); PG8_BAR;
.LBB0_254:
	s_andn2_b64 vcc, exec, s[46:47]
	s_cbranch_vccnz .LBB0_385
	v_bfe_i32 v3, v142, 27, 1
	v_lshlrev_b32_e32 v2, 4, v142
	v_lshrrev_b32_e32 v3, 22, v3
	v_add_u32_e32 v3, v2, v3
	s_cmp_eq_u32 s88, 8
	v_and_b32_e32 v3, 0xfffffc00, v3
	s_cselect_b64 s[6:7], -1, 0
	v_sub_u32_e32 v3, v2, v3
	s_and_b64 s[46:47], s[6:7], exec
	s_brev_b32 s5, 24
	s_mov_b32 s38, 0xa00000
	v_ashrrev_i32_e32 v0, 31, v142
	v_lshrrev_b32_e32 v4, 4, v3
	s_cselect_b32 s5, s5, 0x4000000
	s_cselect_b32 s38, s38, 0x3100000
	s_and_b64 s[46:47], s[44:45], exec
	v_lshrrev_b32_e32 v0, 26, v0
	v_bitop3_b32 v3, v4, v3, 32 bitop3:0x6c
	s_cselect_b32 s38, 0x2b00000, s38
	s_cmp_eq_u32 s88, 3
	v_add_u32_e32 v0, v142, v0
	v_ashrrev_i32_e32 v5, 31, v3
	s_cselect_b64 s[70:71], -1, 0
	v_ashrrev_i32_e32 v0, 6, v0
	v_lshrrev_b32_e32 v5, 26, v5
	s_and_b64 s[46:47], s[70:71], exec
	v_lshlrev_b32_e32 v4, 3, v0
	v_add_u32_e32 v5, v3, v5
	s_cselect_b32 s39, 0x14000000, s5
	s_cselect_b32 s38, 0x800000, s38
	s_or_b64 s[6:7], s[70:71], s[6:7]
	v_and_b32_e32 v4, -16, v4
	v_ashrrev_i32_e32 v6, 6, v5
	v_lshlrev_b32_e32 v0, 5, v0
	s_and_b64 s[6:7], s[6:7], exec
	s_movk_i32 s5, 0x400
	v_add_u32_e32 v4, v6, v4
	v_and_b32_e32 v143, 32, v0
	v_and_b32_e32 v0, 0xc0, v5
	s_cselect_b32 s73, s5, 0xb00
	v_sub_u32_e32 v0, v3, v0
	v_lshlrev_b32_e32 v3, 1, v4
	v_lshrrev_b32_e32 v5, 2, v4
	v_and_b32_e32 v6, 3, v6
	s_mov_b32 s5, 0xffffe0
	v_ashrrev_i16_sdwa v0, v244, sext(v0) dst_sel:DWORD dst_unused:UNUSED_PAD src0_sel:DWORD src1_sel:BYTE_0
	v_and_b32_e32 v3, 24, v3
	v_and_b32_e32 v5, 4, v5
	v_and_or_b32 v6, v4, s5, v6
	v_bfe_i32 v144, v0, 0, 16
	v_or3_b32 v3, v6, v5, v3
	v_add_u32_e32 v0, v143, v144
	v_mul_lo_u32 v145, v4, s73
	v_bfe_u32 v200, v142, 5, 1
	v_mul_i32_i24_e32 v200, 0xffffffd0, v200
	v_ashrrev_i32_e32 v201, 31, v200
	v_mul_u32_u24_e32 v3, s73, v3
	v_add_u32_e32 v2, 0x2000, v2
	v_add_lshl_u32 v194, v0, v145, 1
	v_add_lshl_u32 v0, v3, v0, 1
	v_ashrrev_i32_e32 v3, 31, v2
	v_lshrrev_b32_e32 v3, 22, v3
	v_add_u32_e32 v3, v2, v3
	v_ashrrev_i32_e32 v3, 10, v3
	v_mul_i32_i24_e32 v4, 0x400, v3
	v_sub_u32_e32 v2, v2, v4
	v_lshrrev_b32_e32 v4, 4, v2
	v_bitop3_b32 v2, v4, v2, 32 bitop3:0x6c
	v_ashrrev_i32_e32 v5, 31, v2
	v_lshrrev_b32_e32 v5, 26, v5
	v_lshlrev_b32_e32 v4, 3, v3
	v_add_u32_e32 v5, v2, v5
	v_and_b32_e32 v4, -16, v4
	v_ashrrev_i32_e32 v6, 6, v5
	v_add_u32_e32 v4, v6, v4
	v_and_b32_e32 v6, 3, v6
	s_ashr_i32 s74, s27, 6
	s_ashr_i32 s72, s27, 8
	v_and_or_b32 v6, v4, s5, v6
	s_lshl_b32 s58, s73, 8
	s_lshl_b32 s5, s73, 9
	s_lshl_b32 s6, s74, 10
	s_add_u32 s7, s14, s39
	v_lshlrev_b32_e32 v3, 5, v3
	s_addc_u32 s69, s15, 0
	v_and_b32_e32 v146, 32, v3
	v_and_b32_e32 v3, 0xc0, v5
	s_add_u32 s90, s14, s38
	v_sub_u32_e32 v2, v2, v3
	v_lshlrev_b32_e32 v3, 1, v4
	v_lshrrev_b32_e32 v5, 2, v4
	s_addc_u32 s91, s15, 0
	s_mul_i32 s46, s5, s29
	v_ashrrev_i16_sdwa v2, v244, sext(v2) dst_sel:DWORD dst_unused:UNUSED_PAD src0_sel:DWORD src1_sel:BYTE_0
	v_and_b32_e32 v3, 24, v3
	v_and_b32_e32 v5, 4, v5
	s_mul_hi_i32 s47, s5, s29
	s_add_u32 s46, s90, s46
	v_bfe_i32 v147, v2, 0, 16
	v_or3_b32 v3, v6, v5, v3
	s_addc_u32 s47, s91, s47
	s_add_i32 s92, s6, 0
	v_add_u32_e32 v2, v146, v147
	v_mul_lo_u32 v148, v4, s73
	v_mul_u32_u24_e32 v3, s73, v3
	s_add_i32 m0, s92, 0x10000
	v_add_lshl_u32 v202, v2, v148, 1
	v_add_lshl_u32 v204, v3, v2, 1
	v_mov_b64 v[130:131], 0
	v_mov_b64 v[132:133], 0
	v_mov_b64 v[134:135], 0
	v_mov_b64 v[136:137], 0
	v_mov_b64 v[114:115], 0
	v_mov_b64 v[116:117], 0
	v_mov_b64 v[106:107], 0
	v_mov_b64 v[108:109], 0
	v_mov_b64 v[94:95], 0
	v_mov_b64 v[96:97], 0
	v_mov_b64 v[90:91], 0
	v_mov_b64 v[92:93], 0
	v_mov_b64 v[78:79], 0
	v_mov_b64 v[80:81], 0
	v_mov_b64 v[74:75], 0
	v_mov_b64 v[76:77], 0
	v_mov_b64 v[126:127], 0
	v_mov_b64 v[128:129], 0
	v_mov_b64 v[122:123], 0
	v_mov_b64 v[124:125], 0
	v_mov_b64 v[102:103], 0
	v_mov_b64 v[104:105], 0
	v_mov_b64 v[98:99], 0
	v_mov_b64 v[100:101], 0
	v_mov_b64 v[86:87], 0
	v_mov_b64 v[88:89], 0
	v_mov_b64 v[82:83], 0
	v_mov_b64 v[84:85], 0
	v_mov_b64 v[70:71], 0
	v_mov_b64 v[72:73], 0
	v_mov_b64 v[66:67], 0
	v_mov_b64 v[68:69], 0
	s_waitcnt vmcnt(0)
	v_mov_b64 v[62:63], 0
	v_mov_b64 v[64:65], 0
	v_mov_b64 v[58:59], 0
	v_mov_b64 v[60:61], 0
	v_mov_b64 v[46:47], 0
	v_mov_b64 v[48:49], 0
	v_mov_b64 v[42:43], 0
	v_mov_b64 v[44:45], 0
	v_mov_b64 v[30:31], 0
	v_mov_b64 v[32:33], 0
	v_mov_b64 v[26:27], 0
	v_mov_b64 v[28:29], 0
	v_mov_b64 v[14:15], 0
	v_mov_b64 v[16:17], 0
	v_mov_b64 v[10:11], 0
	v_mov_b64 v[12:13], 0
	v_mov_b64 v[54:55], 0
	v_mov_b64 v[56:57], 0
	v_mov_b64 v[50:51], 0
	v_mov_b64 v[52:53], 0
	v_mov_b64 v[38:39], 0
	v_mov_b64 v[40:41], 0
	v_mov_b64 v[34:35], 0
	v_mov_b64 v[36:37], 0
	v_mov_b64 v[22:23], 0
	v_mov_b64 v[24:25], 0
	v_mov_b64 v[18:19], 0
	v_mov_b64 v[20:21], 0
	v_mov_b64 v[6:7], 0
	v_mov_b64 v[8:9], 0
	v_mov_b64 v[2:3], 0
	v_mov_b64 v[4:5], 0
	global_load_lds_dwordx4 v0, s[46:47]
	s_add_i32 m0, s92, 0x12000
	s_add_u32 s48, s46, s58
	global_load_lds_dwordx4 v204, s[46:47]
	s_addc_u32 s49, s47, 0
	s_add_i32 m0, s92, 0x14000
	s_mul_i32 s39, s5, s33
	v_mov_b32_e32 v205, v1
	global_load_lds_dwordx4 v0, s[48:49]
	s_add_i32 m0, s92, 0x16000
	s_mul_hi_i32 s38, s5, s33
	v_lshl_add_u64 v[118:119], s[48:49], 0, v[0:1]
	v_lshl_add_u64 v[120:121], s[48:49], 0, v[204:205]
	global_load_lds_dwordx4 v204, s[48:49]
	s_add_u32 s48, s7, s39
	s_addc_u32 s49, s69, s38
	s_add_i32 s93, s92, 0x2000
	s_mov_b32 m0, s92
	s_add_u32 s60, s48, s58
	global_load_lds_dwordx4 v194, s[48:49]
	s_mov_b32 m0, s93
	s_addc_u32 s61, s49, 0
	s_add_i32 s94, s92, 0x4000
	global_load_lds_dwordx4 v202, s[48:49]
	s_mov_b32 m0, s94
	s_add_i32 s95, s92, 0x6000
	global_load_lds_dwordx4 v194, s[60:61]
	s_mov_b32 m0, s95
	v_mov_b32_e32 v195, v1
	global_load_lds_dwordx4 v202, s[60:61]
	v_mov_b32_e32 v203, v1
	s_cmp_eq_u32 s72, 1
	v_mov_b32_e32 v241, v240
	v_mov_b32_e32 v240, v239
	v_mov_b32_e32 v239, v238
	v_mov_b32_e32 v238, v233
	v_mov_b32_e32 v233, v245
	v_mov_b32_e32 v252, 1
	v_lshl_add_u64 v[110:111], s[46:47], 0, v[0:1]
	v_lshl_add_u64 v[112:113], s[46:47], 0, v[204:205]
	v_lshl_add_u64 v[138:139], s[48:49], 0, v[194:195]
	v_lshl_add_u64 v[140:141], s[48:49], 0, v[202:203]
	s_cselect_b64 s[60:61], -1, 0
	s_cmp_lg_u32 s72, 1
	s_cbranch_scc1 .LBB0_257
	s_barrier

; #define EPIRES_LOAD(slot, q) do { _Pragma("unroll") for (int mm = 0; mm < 2; ++mm) { const size_t off_ = (size_t)(row0 + ((q) >> 1) * HALF + (2 * ((q) & 1) + mm) * 16) * 1024 + col0; \
;             _Pragma("unroll") for (int bj = 0; bj < 2; ++bj) { \
;                 pre[slot][mm][bj] = *(const u32x4*)(res16 + off_ + bj * HALF); } } } while (0)
;     __device__ __forceinline__ void operator()(const f32x4 (&acc)[2][2][4][2], const Unit& u, int wr, int wc, int fr, int fq, PG8_LAS unsigned char* lds, int& rs_pm, int& rs_tog) const {
;         const int row0 = u.pm * BM + wr * 64 + fr, col0 = u.pn * BM + wc * 32 + 8 * fq;
;         u32x4 pre[4][2][2];
;     ...
;         EPIRES_LOAD(0, 0); EPIRES_LOAD(1, 1); EPIRES_LOAD(2, 2); EPIRES_LOAD(3, 3);
; #pragma unroll
;         for (int q = 0; q < 4; ++q) {
;             const int ai = q >> 1, slot = q;
; #pragma unroll
;             for (int mm = 0; mm < 2; ++mm) {
;                 const int m = 2 * (q & 1) + mm; const size_t off = (size_t)(row0 + ai * HALF + m * 16) * 1024 + col0; float qs = 0.f;
; #pragma unroll
;                 for (int bj = 0; bj < 2; ++bj) {
;                     const u32x4 w_ = pre[slot][mm][bj];
;                     const f32x4 r0 = (f32x4){__uint_as_float(w_.x << 16), __uint_as_float(w_.x & 0xffff0000u), __uint_as_float(w_.y << 16), __uint_as_float(w_.y & 0xffff0000u)};
;                     const f32x4 r1 = (f32x4){__uint_as_float(w_.z << 16), __uint_as_float(w_.z & 0xffff0000u), __uint_as_float(w_.w << 16), __uint_as_float(w_.w & 0xffff0000u)};
;                     const f32x4 v0 = acc[ai][bj][m][0] + r0, v1 = acc[ai][bj][m][1] + r1;
;                     if (out32) { *(f32x4*)(out32 + off + bj * HALF) = v0; *(f32x4*)(out32 + off + bj * HALF + 4) = v1; }
.LBB0_277:
	v_lshl_add_u32 v210, s33, 8, v244
	v_lshl_or_b32 v212, s29, 8, v246
	v_ashrrev_i32_e32 v213, 31, v212
	v_ashrrev_i32_e32 v211, 31, v210
	v_lshl_add_u64 v[110:111], v[212:213], 1, s[70:71]
	v_lshlrev_b64 v[112:113], 11, v[210:211]
	v_or_b32_e32 v226, 16, v210
	v_lshl_add_u64 v[112:113], v[110:111], 0, v[112:113]
	v_ashrrev_i32_e32 v227, 31, v226
	global_load_dwordx4 v[190:193], v[112:113], off
	global_load_dwordx4 v[186:189], v[112:113], off offset:256
	v_lshlrev_b64 v[112:113], 11, v[226:227]
	v_or_b32_e32 v224, 32, v210
	v_lshl_add_u64 v[112:113], v[110:111], 0, v[112:113]
	v_ashrrev_i32_e32 v225, 31, v224
	global_load_dwordx4 v[182:185], v[112:113], off
	global_load_dwordx4 v[178:181], v[112:113], off offset:256
	v_lshlrev_b64 v[112:113], 11, v[224:225]
	v_or_b32_e32 v222, 48, v210
	v_lshl_add_u64 v[112:113], v[110:111], 0, v[112:113]
	v_ashrrev_i32_e32 v223, 31, v222
	global_load_dwordx4 v[174:177], v[112:113], off
	global_load_dwordx4 v[170:173], v[112:113], off offset:256
	v_lshlrev_b64 v[112:113], 11, v[222:223]
	v_add_u32_e32 v220, 0x80, v210
	v_lshl_add_u64 v[112:113], v[110:111], 0, v[112:113]
	v_ashrrev_i32_e32 v221, 31, v220
	global_load_dwordx4 v[166:169], v[112:113], off
	global_load_dwordx4 v[162:165], v[112:113], off offset:256
	v_lshlrev_b64 v[112:113], 11, v[220:221]
	v_add_u32_e32 v218, 0x90, v210
	v_lshl_add_u64 v[112:113], v[110:111], 0, v[112:113]
	v_ashrrev_i32_e32 v219, 31, v218
	global_load_dwordx4 v[158:161], v[112:113], off
	global_load_dwordx4 v[154:157], v[112:113], off offset:256
	v_lshlrev_b64 v[112:113], 11, v[218:219]
	v_add_u32_e32 v216, 0xa0, v210
	v_lshl_add_u64 v[112:113], v[110:111], 0, v[112:113]
	v_ashrrev_i32_e32 v217, 31, v216
	global_load_dwordx4 v[150:153], v[112:113], off
	global_load_dwordx4 v[146:149], v[112:113], off offset:256
	v_lshlrev_b64 v[112:113], 11, v[216:217]
	v_add_u32_e32 v214, 0xb0, v210
	v_lshl_add_u64 v[112:113], v[110:111], 0, v[112:113]
	v_ashrrev_i32_e32 v215, 31, v214
	global_load_dwordx4 v[142:145], v[112:113], off
	global_load_dwordx4 v[138:141], v[112:113], off offset:256
	v_lshlrev_b64 v[112:113], 11, v[214:215]
	v_lshl_add_u64 v[110:111], v[110:111], 0, v[112:113]
	global_load_dwordx4 v[118:121], v[110:111], off
	s_nop 0
	global_load_dwordx4 v[110:113], v[110:111], off offset:256
	v_cndmask_b32_e64 v228, 0, 1, s[74:75]
	v_cmp_ne_u32_e64 s[46:47], 1, v228
	v_lshlrev_b64 v[228:229], 10, v[210:211]
	v_lshl_add_u64 v[228:229], v[228:229], 0, v[212:213]
	s_andn2_b64 vcc, exec, s[74:75]
	s_waitcnt vmcnt(0)
	v_lshlrev_b32_e32 v248, 16, v190
	v_and_b32_e32 v249, 0xffff0000, v190
	v_lshlrev_b32_e32 v190, 16, v191
	v_and_b32_e32 v191, 0xffff0000, v191
	v_lshlrev_b32_e32 v250, 16, v192
	v_and_b32_e32 v251, 0xffff0000, v192
	v_lshlrev_b32_e32 v236, 16, v193
	v_and_b32_e32 v237, 0xffff0000, v193
	v_pk_add_f32 v[192:193], v[132:133], v[190:191]
	v_pk_add_f32 v[190:191], v[130:131], v[248:249]
	v_pk_add_f32 v[132:133], v[136:137], v[236:237]
	v_pk_add_f32 v[130:131], v[134:135], v[250:251]
	v_lshl_add_u64 v[136:137], v[228:229], 2, s[10:11]
	v_lshl_add_u64 v[136:137], v[136:137], 0, v[200:201]
	s_cbranch_vccnz .LBB0_279
	s_nop 1
	v_permlane32_swap_b32_e32 v190, v130
	v_permlane32_swap_b32_e32 v191, v131
	v_permlane32_swap_b32_e32 v192, v132
	v_permlane32_swap_b32_e32 v193, v133
	global_store_dwordx4 v[136:137], v[190:193], off
	global_store_dwordx4 v[136:137], v[130:133], off offset:64

;     __device__ __forceinline__ void operator()(const f32x4 (&acc)[2][2][4][2], const Unit& u, int wr, int wc, int fr, int fq, PG8_LAS unsigned char* lds, int& rs_pm, int& rs_tog) const {
;     ...
;                     const u32x4 w_ = pre[slot][mm][bj];
;                     const f32x4 r0 = (f32x4){__uint_as_float(w_.x << 16), __uint_as_float(w_.x & 0xffff0000u), __uint_as_float(w_.y << 16), __uint_as_float(w_.y & 0xffff0000u)};
;                     const f32x4 r1 = (f32x4){__uint_as_float(w_.z << 16), __uint_as_float(w_.z & 0xffff0000u), __uint_as_float(w_.w << 16), __uint_as_float(w_.w & 0xffff0000u)};
;                     const f32x4 v0 = acc[ai][bj][m][0] + r0, v1 = acc[ai][bj][m][1] + r1;
;                     if (out32) { *(f32x4*)(out32 + off + bj * HALF) = v0; *(f32x4*)(out32 + off + bj * HALF + 4) = v1; }
.LBB0_282:
	v_lshlrev_b32_e32 v132, 16, v186
	v_and_b32_e32 v133, 0xffff0000, v186
	v_lshlrev_b32_e32 v186, 16, v187
	v_and_b32_e32 v187, 0xffff0000, v187
	v_lshlrev_b32_e32 v190, 16, v188
	v_and_b32_e32 v191, 0xffff0000, v188
	v_lshlrev_b32_e32 v188, 16, v189
	v_and_b32_e32 v189, 0xffff0000, v189
	v_pk_add_f32 v[128:129], v[128:129], v[186:187]
	v_pk_add_f32 v[126:127], v[126:127], v[132:133]
	v_pk_add_f32 v[124:125], v[124:125], v[188:189]
	s_and_b64 vcc, exec, s[46:47]
	v_pk_add_f32 v[122:123], v[122:123], v[190:191]
	s_cbranch_vccnz .LBB0_284
	s_nop 1
	v_permlane32_swap_b32_e32 v126, v122
	v_permlane32_swap_b32_e32 v127, v123
	v_permlane32_swap_b32_e32 v128, v124
	v_permlane32_swap_b32_e32 v129, v125
	global_store_dwordx4 v[136:137], v[126:129], off offset:512
	global_store_dwordx4 v[136:137], v[122:125], off offset:576

;     __device__ __forceinline__ void operator()(const f32x4 (&acc)[2][2][4][2], const Unit& u, int wr, int wc, int fr, int fq, PG8_LAS unsigned char* lds, int& rs_pm, int& rs_tog) const {
;     ...
;                     const u32x4 w_ = pre[slot][mm][bj];
;                     const f32x4 r0 = (f32x4){__uint_as_float(w_.x << 16), __uint_as_float(w_.x & 0xffff0000u), __uint_as_float(w_.y << 16), __uint_as_float(w_.y & 0xffff0000u)};
;                     const f32x4 r1 = (f32x4){__uint_as_float(w_.z << 16), __uint_as_float(w_.z & 0xffff0000u), __uint_as_float(w_.w << 16), __uint_as_float(w_.w & 0xffff0000u)};
;                     const f32x4 v0 = acc[ai][bj][m][0] + r0, v1 = acc[ai][bj][m][1] + r1;
;                     if (out32) { *(f32x4*)(out32 + off + bj * HALF) = v0; *(f32x4*)(out32 + off + bj * HALF + 4) = v1; }
.LBB0_290:
	s_waitcnt lgkmcnt(0)
	v_lshlrev_b64 v[122:123], 10, v[226:227]
	v_lshl_add_u64 v[122:123], v[122:123], 0, v[212:213]
	v_lshlrev_b32_e32 v124, 16, v182
	v_and_b32_e32 v125, 0xffff0000, v182
	v_lshlrev_b32_e32 v126, 16, v183
	v_and_b32_e32 v127, 0xffff0000, v183
	v_lshlrev_b32_e32 v128, 16, v184
	v_and_b32_e32 v129, 0xffff0000, v184
	v_lshlrev_b32_e32 v130, 16, v185
	v_and_b32_e32 v131, 0xffff0000, v185
	v_pk_add_f32 v[116:117], v[116:117], v[126:127]
	v_pk_add_f32 v[114:115], v[114:115], v[124:125]
	v_pk_add_f32 v[108:109], v[108:109], v[130:131]
	v_pk_add_f32 v[106:107], v[106:107], v[128:129]
	s_and_b64 vcc, exec, s[46:47]
	v_lshl_add_u64 v[124:125], v[122:123], 2, s[10:11]
	v_lshl_add_u64 v[124:125], v[124:125], 0, v[200:201]
	s_cbranch_vccnz .LBB0_292
	s_nop 1
	v_permlane32_swap_b32_e32 v114, v106
	v_permlane32_swap_b32_e32 v115, v107
	v_permlane32_swap_b32_e32 v116, v108
	v_permlane32_swap_b32_e32 v117, v109
	global_store_dwordx4 v[124:125], v[114:117], off
	global_store_dwordx4 v[124:125], v[106:109], off offset:64

;     __device__ __forceinline__ void operator()(const f32x4 (&acc)[2][2][4][2], const Unit& u, int wr, int wc, int fr, int fq, PG8_LAS unsigned char* lds, int& rs_pm, int& rs_tog) const {
;     ...
;                     const u32x4 w_ = pre[slot][mm][bj];
;                     const f32x4 r0 = (f32x4){__uint_as_float(w_.x << 16), __uint_as_float(w_.x & 0xffff0000u), __uint_as_float(w_.y << 16), __uint_as_float(w_.y & 0xffff0000u)};
;                     const f32x4 r1 = (f32x4){__uint_as_float(w_.z << 16), __uint_as_float(w_.z & 0xffff0000u), __uint_as_float(w_.w << 16), __uint_as_float(w_.w & 0xffff0000u)};
;                     const f32x4 v0 = acc[ai][bj][m][0] + r0, v1 = acc[ai][bj][m][1] + r1;
;                     if (out32) { *(f32x4*)(out32 + off + bj * HALF) = v0; *(f32x4*)(out32 + off + bj * HALF + 4) = v1; }
.LBB0_295:
	v_lshlrev_b32_e32 v108, 16, v178
	v_and_b32_e32 v109, 0xffff0000, v178
	v_lshlrev_b32_e32 v114, 16, v179
	v_and_b32_e32 v115, 0xffff0000, v179
	v_lshlrev_b32_e32 v116, 16, v180
	v_and_b32_e32 v117, 0xffff0000, v180
	v_lshlrev_b32_e32 v126, 16, v181
	v_and_b32_e32 v127, 0xffff0000, v181
	v_pk_add_f32 v[104:105], v[104:105], v[114:115]
	v_pk_add_f32 v[102:103], v[102:103], v[108:109]
	v_pk_add_f32 v[100:101], v[100:101], v[126:127]
	s_and_b64 vcc, exec, s[46:47]
	v_pk_add_f32 v[98:99], v[98:99], v[116:117]
	s_cbranch_vccnz .LBB0_297
	s_nop 1
	v_permlane32_swap_b32_e32 v102, v98
	v_permlane32_swap_b32_e32 v103, v99
	v_permlane32_swap_b32_e32 v104, v100
	v_permlane32_swap_b32_e32 v105, v101
	global_store_dwordx4 v[124:125], v[102:105], off offset:512
	global_store_dwordx4 v[124:125], v[98:101], off offset:576

;     __device__ __forceinline__ void operator()(const f32x4 (&acc)[2][2][4][2], const Unit& u, int wr, int wc, int fr, int fq, PG8_LAS unsigned char* lds, int& rs_pm, int& rs_tog) const {
;     ...
;                     const u32x4 w_ = pre[slot][mm][bj];
;                     const f32x4 r0 = (f32x4){__uint_as_float(w_.x << 16), __uint_as_float(w_.x & 0xffff0000u), __uint_as_float(w_.y << 16), __uint_as_float(w_.y & 0xffff0000u)};
;                     const f32x4 r1 = (f32x4){__uint_as_float(w_.z << 16), __uint_as_float(w_.z & 0xffff0000u), __uint_as_float(w_.w << 16), __uint_as_float(w_.w & 0xffff0000u)};
;                     const f32x4 v0 = acc[ai][bj][m][0] + r0, v1 = acc[ai][bj][m][1] + r1;
;                     if (out32) { *(f32x4*)(out32 + off + bj * HALF) = v0; *(f32x4*)(out32 + off + bj * HALF + 4) = v1; }
.LBB0_303:
	s_waitcnt lgkmcnt(0)
	v_lshlrev_b64 v[98:99], 10, v[224:225]
	v_lshl_add_u64 v[98:99], v[98:99], 0, v[212:213]
	v_lshlrev_b32_e32 v100, 16, v174
	v_and_b32_e32 v101, 0xffff0000, v174
	v_lshlrev_b32_e32 v102, 16, v175
	v_and_b32_e32 v103, 0xffff0000, v175
	v_lshlrev_b32_e32 v104, 16, v176
	v_and_b32_e32 v105, 0xffff0000, v176
	v_lshlrev_b32_e32 v106, 16, v177
	v_and_b32_e32 v107, 0xffff0000, v177
	v_pk_add_f32 v[96:97], v[96:97], v[102:103]
	v_pk_add_f32 v[94:95], v[94:95], v[100:101]
	v_pk_add_f32 v[92:93], v[92:93], v[106:107]
	v_pk_add_f32 v[90:91], v[90:91], v[104:105]
	s_and_b64 vcc, exec, s[46:47]
	v_lshl_add_u64 v[100:101], v[98:99], 2, s[10:11]
	v_lshl_add_u64 v[100:101], v[100:101], 0, v[200:201]
	s_cbranch_vccnz .LBB0_305
	s_nop 1
	v_permlane32_swap_b32_e32 v94, v90
	v_permlane32_swap_b32_e32 v95, v91
	v_permlane32_swap_b32_e32 v96, v92
	v_permlane32_swap_b32_e32 v97, v93
	global_store_dwordx4 v[100:101], v[94:97], off
	global_store_dwordx4 v[100:101], v[90:93], off offset:64

;     __device__ __forceinline__ void operator()(const f32x4 (&acc)[2][2][4][2], const Unit& u, int wr, int wc, int fr, int fq, PG8_LAS unsigned char* lds, int& rs_pm, int& rs_tog) const {
;     ...
;                     const u32x4 w_ = pre[slot][mm][bj];
;                     const f32x4 r0 = (f32x4){__uint_as_float(w_.x << 16), __uint_as_float(w_.x & 0xffff0000u), __uint_as_float(w_.y << 16), __uint_as_float(w_.y & 0xffff0000u)};
;                     const f32x4 r1 = (f32x4){__uint_as_float(w_.z << 16), __uint_as_float(w_.z & 0xffff0000u), __uint_as_float(w_.w << 16), __uint_as_float(w_.w & 0xffff0000u)};
;                     const f32x4 v0 = acc[ai][bj][m][0] + r0, v1 = acc[ai][bj][m][1] + r1;
;                     if (out32) { *(f32x4*)(out32 + off + bj * HALF) = v0; *(f32x4*)(out32 + off + bj * HALF + 4) = v1; }
.LBB0_308:
	v_lshlrev_b32_e32 v92, 16, v170
	v_and_b32_e32 v93, 0xffff0000, v170
	v_lshlrev_b32_e32 v94, 16, v171
	v_and_b32_e32 v95, 0xffff0000, v171
	v_lshlrev_b32_e32 v96, 16, v172
	v_and_b32_e32 v97, 0xffff0000, v172
	v_lshlrev_b32_e32 v102, 16, v173
	v_and_b32_e32 v103, 0xffff0000, v173
	v_pk_add_f32 v[88:89], v[88:89], v[94:95]
	v_pk_add_f32 v[86:87], v[86:87], v[92:93]
	v_pk_add_f32 v[84:85], v[84:85], v[102:103]
	s_and_b64 vcc, exec, s[46:47]
	v_pk_add_f32 v[82:83], v[82:83], v[96:97]
	s_cbranch_vccnz .LBB0_310
	s_nop 1
	v_permlane32_swap_b32_e32 v86, v82
	v_permlane32_swap_b32_e32 v87, v83
	v_permlane32_swap_b32_e32 v88, v84
	v_permlane32_swap_b32_e32 v89, v85
	global_store_dwordx4 v[100:101], v[86:89], off offset:512
	global_store_dwordx4 v[100:101], v[82:85], off offset:576

;     __device__ __forceinline__ void operator()(const f32x4 (&acc)[2][2][4][2], const Unit& u, int wr, int wc, int fr, int fq, PG8_LAS unsigned char* lds, int& rs_pm, int& rs_tog) const {
;     ...
;                     const u32x4 w_ = pre[slot][mm][bj];
;                     const f32x4 r0 = (f32x4){__uint_as_float(w_.x << 16), __uint_as_float(w_.x & 0xffff0000u), __uint_as_float(w_.y << 16), __uint_as_float(w_.y & 0xffff0000u)};
;                     const f32x4 r1 = (f32x4){__uint_as_float(w_.z << 16), __uint_as_float(w_.z & 0xffff0000u), __uint_as_float(w_.w << 16), __uint_as_float(w_.w & 0xffff0000u)};
;                     const f32x4 v0 = acc[ai][bj][m][0] + r0, v1 = acc[ai][bj][m][1] + r1;
;                     if (out32) { *(f32x4*)(out32 + off + bj * HALF) = v0; *(f32x4*)(out32 + off + bj * HALF + 4) = v1; }
.LBB0_316:
	s_waitcnt lgkmcnt(0)
	v_lshlrev_b64 v[82:83], 10, v[222:223]
	v_lshl_add_u64 v[82:83], v[82:83], 0, v[212:213]
	v_lshlrev_b32_e32 v84, 16, v166
	v_and_b32_e32 v85, 0xffff0000, v166
	v_lshlrev_b32_e32 v86, 16, v167
	v_and_b32_e32 v87, 0xffff0000, v167
	v_lshlrev_b32_e32 v88, 16, v168
	v_and_b32_e32 v89, 0xffff0000, v168
	v_lshlrev_b32_e32 v90, 16, v169
	v_and_b32_e32 v91, 0xffff0000, v169
	v_pk_add_f32 v[80:81], v[80:81], v[86:87]
	v_pk_add_f32 v[78:79], v[78:79], v[84:85]
	v_pk_add_f32 v[76:77], v[76:77], v[90:91]
	v_pk_add_f32 v[74:75], v[74:75], v[88:89]
	s_and_b64 vcc, exec, s[46:47]
	v_lshl_add_u64 v[84:85], v[82:83], 2, s[10:11]
	v_lshl_add_u64 v[84:85], v[84:85], 0, v[200:201]
	s_cbranch_vccnz .LBB0_318
	s_nop 1
	v_permlane32_swap_b32_e32 v78, v74
	v_permlane32_swap_b32_e32 v79, v75
	v_permlane32_swap_b32_e32 v80, v76
	v_permlane32_swap_b32_e32 v81, v77
	global_store_dwordx4 v[84:85], v[78:81], off
	global_store_dwordx4 v[84:85], v[74:77], off offset:64

;     __device__ __forceinline__ void operator()(const f32x4 (&acc)[2][2][4][2], const Unit& u, int wr, int wc, int fr, int fq, PG8_LAS unsigned char* lds, int& rs_pm, int& rs_tog) const {
;     ...
;                     const u32x4 w_ = pre[slot][mm][bj];
;                     const f32x4 r0 = (f32x4){__uint_as_float(w_.x << 16), __uint_as_float(w_.x & 0xffff0000u), __uint_as_float(w_.y << 16), __uint_as_float(w_.y & 0xffff0000u)};
;                     const f32x4 r1 = (f32x4){__uint_as_float(w_.z << 16), __uint_as_float(w_.z & 0xffff0000u), __uint_as_float(w_.w << 16), __uint_as_float(w_.w & 0xffff0000u)};
;                     const f32x4 v0 = acc[ai][bj][m][0] + r0, v1 = acc[ai][bj][m][1] + r1;
;                     if (out32) { *(f32x4*)(out32 + off + bj * HALF) = v0; *(f32x4*)(out32 + off + bj * HALF + 4) = v1; }
.LBB0_321:
	v_lshlrev_b32_e32 v76, 16, v162
	v_and_b32_e32 v77, 0xffff0000, v162
	v_lshlrev_b32_e32 v78, 16, v163
	v_and_b32_e32 v79, 0xffff0000, v163
	v_lshlrev_b32_e32 v80, 16, v164
	v_and_b32_e32 v81, 0xffff0000, v164
	v_lshlrev_b32_e32 v86, 16, v165
	v_and_b32_e32 v87, 0xffff0000, v165
	v_pk_add_f32 v[72:73], v[72:73], v[78:79]
	v_pk_add_f32 v[70:71], v[70:71], v[76:77]
	v_pk_add_f32 v[68:69], v[68:69], v[86:87]
	s_and_b64 vcc, exec, s[46:47]
	v_pk_add_f32 v[66:67], v[66:67], v[80:81]
	s_cbranch_vccnz .LBB0_323
	s_nop 1
	v_permlane32_swap_b32_e32 v70, v66
	v_permlane32_swap_b32_e32 v71, v67
	v_permlane32_swap_b32_e32 v72, v68
	v_permlane32_swap_b32_e32 v73, v69
	global_store_dwordx4 v[84:85], v[70:73], off offset:512
	global_store_dwordx4 v[84:85], v[66:69], off offset:576

;     __device__ __forceinline__ void operator()(const f32x4 (&acc)[2][2][4][2], const Unit& u, int wr, int wc, int fr, int fq, PG8_LAS unsigned char* lds, int& rs_pm, int& rs_tog) const {
;     ...
;                     const u32x4 w_ = pre[slot][mm][bj];
;                     const f32x4 r0 = (f32x4){__uint_as_float(w_.x << 16), __uint_as_float(w_.x & 0xffff0000u), __uint_as_float(w_.y << 16), __uint_as_float(w_.y & 0xffff0000u)};
;                     const f32x4 r1 = (f32x4){__uint_as_float(w_.z << 16), __uint_as_float(w_.z & 0xffff0000u), __uint_as_float(w_.w << 16), __uint_as_float(w_.w & 0xffff0000u)};
;                     const f32x4 v0 = acc[ai][bj][m][0] + r0, v1 = acc[ai][bj][m][1] + r1;
;                     if (out32) { *(f32x4*)(out32 + off + bj * HALF) = v0; *(f32x4*)(out32 + off + bj * HALF + 4) = v1; }
.LBB0_329:
	s_waitcnt lgkmcnt(0)
	v_lshlrev_b64 v[66:67], 10, v[220:221]
	v_lshl_add_u64 v[66:67], v[66:67], 0, v[212:213]
	v_lshlrev_b32_e32 v68, 16, v158
	v_and_b32_e32 v69, 0xffff0000, v158
	v_lshlrev_b32_e32 v70, 16, v159
	v_and_b32_e32 v71, 0xffff0000, v159
	v_lshlrev_b32_e32 v72, 16, v160
	v_and_b32_e32 v73, 0xffff0000, v160
	v_lshlrev_b32_e32 v74, 16, v161
	v_and_b32_e32 v75, 0xffff0000, v161
	v_pk_add_f32 v[64:65], v[64:65], v[70:71]
	v_pk_add_f32 v[62:63], v[62:63], v[68:69]
	v_pk_add_f32 v[60:61], v[60:61], v[74:75]
	v_pk_add_f32 v[58:59], v[58:59], v[72:73]
	s_and_b64 vcc, exec, s[46:47]
	v_lshl_add_u64 v[68:69], v[66:67], 2, s[10:11]
	v_lshl_add_u64 v[68:69], v[68:69], 0, v[200:201]
	s_cbranch_vccnz .LBB0_331
	s_nop 1
	v_permlane32_swap_b32_e32 v62, v58
	v_permlane32_swap_b32_e32 v63, v59
	v_permlane32_swap_b32_e32 v64, v60
	v_permlane32_swap_b32_e32 v65, v61
	global_store_dwordx4 v[68:69], v[62:65], off
	global_store_dwordx4 v[68:69], v[58:61], off offset:64

;     __device__ __forceinline__ void operator()(const f32x4 (&acc)[2][2][4][2], const Unit& u, int wr, int wc, int fr, int fq, PG8_LAS unsigned char* lds, int& rs_pm, int& rs_tog) const {
;     ...
;                     const u32x4 w_ = pre[slot][mm][bj];
;                     const f32x4 r0 = (f32x4){__uint_as_float(w_.x << 16), __uint_as_float(w_.x & 0xffff0000u), __uint_as_float(w_.y << 16), __uint_as_float(w_.y & 0xffff0000u)};
;                     const f32x4 r1 = (f32x4){__uint_as_float(w_.z << 16), __uint_as_float(w_.z & 0xffff0000u), __uint_as_float(w_.w << 16), __uint_as_float(w_.w & 0xffff0000u)};
;                     const f32x4 v0 = acc[ai][bj][m][0] + r0, v1 = acc[ai][bj][m][1] + r1;
;                     if (out32) { *(f32x4*)(out32 + off + bj * HALF) = v0; *(f32x4*)(out32 + off + bj * HALF + 4) = v1; }
.LBB0_334:
	v_lshlrev_b32_e32 v60, 16, v154
	v_and_b32_e32 v61, 0xffff0000, v154
	v_lshlrev_b32_e32 v62, 16, v155
	v_and_b32_e32 v63, 0xffff0000, v155
	v_lshlrev_b32_e32 v64, 16, v156
	v_and_b32_e32 v65, 0xffff0000, v156
	v_lshlrev_b32_e32 v70, 16, v157
	v_and_b32_e32 v71, 0xffff0000, v157
	v_pk_add_f32 v[56:57], v[56:57], v[62:63]
	v_pk_add_f32 v[54:55], v[54:55], v[60:61]
	v_pk_add_f32 v[52:53], v[52:53], v[70:71]
	s_and_b64 vcc, exec, s[46:47]
	v_pk_add_f32 v[50:51], v[50:51], v[64:65]
	s_cbranch_vccnz .LBB0_336
	s_nop 1
	v_permlane32_swap_b32_e32 v54, v50
	v_permlane32_swap_b32_e32 v55, v51
	v_permlane32_swap_b32_e32 v56, v52
	v_permlane32_swap_b32_e32 v57, v53
	global_store_dwordx4 v[68:69], v[54:57], off offset:512
	global_store_dwordx4 v[68:69], v[50:53], off offset:576

;     __device__ __forceinline__ void operator()(const f32x4 (&acc)[2][2][4][2], const Unit& u, int wr, int wc, int fr, int fq, PG8_LAS unsigned char* lds, int& rs_pm, int& rs_tog) const {
;     ...
;                     const u32x4 w_ = pre[slot][mm][bj];
;                     const f32x4 r0 = (f32x4){__uint_as_float(w_.x << 16), __uint_as_float(w_.x & 0xffff0000u), __uint_as_float(w_.y << 16), __uint_as_float(w_.y & 0xffff0000u)};
;                     const f32x4 r1 = (f32x4){__uint_as_float(w_.z << 16), __uint_as_float(w_.z & 0xffff0000u), __uint_as_float(w_.w << 16), __uint_as_float(w_.w & 0xffff0000u)};
;                     const f32x4 v0 = acc[ai][bj][m][0] + r0, v1 = acc[ai][bj][m][1] + r1;
;                     if (out32) { *(f32x4*)(out32 + off + bj * HALF) = v0; *(f32x4*)(out32 + off + bj * HALF + 4) = v1; }
.LBB0_342:
	s_waitcnt lgkmcnt(0)
	v_lshlrev_b64 v[50:51], 10, v[218:219]
	v_lshl_add_u64 v[50:51], v[50:51], 0, v[212:213]
	v_lshlrev_b32_e32 v52, 16, v150
	v_and_b32_e32 v53, 0xffff0000, v150
	v_lshlrev_b32_e32 v54, 16, v151
	v_and_b32_e32 v55, 0xffff0000, v151
	v_lshlrev_b32_e32 v56, 16, v152
	v_and_b32_e32 v57, 0xffff0000, v152
	v_lshlrev_b32_e32 v58, 16, v153
	v_and_b32_e32 v59, 0xffff0000, v153
	v_pk_add_f32 v[48:49], v[48:49], v[54:55]
	v_pk_add_f32 v[46:47], v[46:47], v[52:53]
	v_pk_add_f32 v[44:45], v[44:45], v[58:59]
	v_pk_add_f32 v[42:43], v[42:43], v[56:57]
	s_and_b64 vcc, exec, s[46:47]
	v_lshl_add_u64 v[52:53], v[50:51], 2, s[10:11]
	v_lshl_add_u64 v[52:53], v[52:53], 0, v[200:201]
	s_cbranch_vccnz .LBB0_344
	s_nop 1
	v_permlane32_swap_b32_e32 v46, v42
	v_permlane32_swap_b32_e32 v47, v43
	v_permlane32_swap_b32_e32 v48, v44
	v_permlane32_swap_b32_e32 v49, v45
	global_store_dwordx4 v[52:53], v[46:49], off
	global_store_dwordx4 v[52:53], v[42:45], off offset:64

;     __device__ __forceinline__ void operator()(const f32x4 (&acc)[2][2][4][2], const Unit& u, int wr, int wc, int fr, int fq, PG8_LAS unsigned char* lds, int& rs_pm, int& rs_tog) const {
;     ...
;                     const u32x4 w_ = pre[slot][mm][bj];
;                     const f32x4 r0 = (f32x4){__uint_as_float(w_.x << 16), __uint_as_float(w_.x & 0xffff0000u), __uint_as_float(w_.y << 16), __uint_as_float(w_.y & 0xffff0000u)};
;                     const f32x4 r1 = (f32x4){__uint_as_float(w_.z << 16), __uint_as_float(w_.z & 0xffff0000u), __uint_as_float(w_.w << 16), __uint_as_float(w_.w & 0xffff0000u)};
;                     const f32x4 v0 = acc[ai][bj][m][0] + r0, v1 = acc[ai][bj][m][1] + r1;
;                     if (out32) { *(f32x4*)(out32 + off + bj * HALF) = v0; *(f32x4*)(out32 + off + bj * HALF + 4) = v1; }
.LBB0_347:
	v_lshlrev_b32_e32 v44, 16, v146
	v_and_b32_e32 v45, 0xffff0000, v146
	v_lshlrev_b32_e32 v46, 16, v147
	v_and_b32_e32 v47, 0xffff0000, v147
	v_lshlrev_b32_e32 v48, 16, v148
	v_and_b32_e32 v49, 0xffff0000, v148
	v_lshlrev_b32_e32 v54, 16, v149
	v_and_b32_e32 v55, 0xffff0000, v149
	v_pk_add_f32 v[40:41], v[40:41], v[46:47]
	v_pk_add_f32 v[38:39], v[38:39], v[44:45]
	v_pk_add_f32 v[36:37], v[36:37], v[54:55]
	s_and_b64 vcc, exec, s[46:47]
	v_pk_add_f32 v[34:35], v[34:35], v[48:49]
	s_cbranch_vccnz .LBB0_349
	s_nop 1
	v_permlane32_swap_b32_e32 v38, v34
	v_permlane32_swap_b32_e32 v39, v35
	v_permlane32_swap_b32_e32 v40, v36
	v_permlane32_swap_b32_e32 v41, v37
	global_store_dwordx4 v[52:53], v[38:41], off offset:512
	global_store_dwordx4 v[52:53], v[34:37], off offset:576

;     __device__ __forceinline__ void operator()(const f32x4 (&acc)[2][2][4][2], const Unit& u, int wr, int wc, int fr, int fq, PG8_LAS unsigned char* lds, int& rs_pm, int& rs_tog) const {
;     ...
;                     const u32x4 w_ = pre[slot][mm][bj];
;                     const f32x4 r0 = (f32x4){__uint_as_float(w_.x << 16), __uint_as_float(w_.x & 0xffff0000u), __uint_as_float(w_.y << 16), __uint_as_float(w_.y & 0xffff0000u)};
;                     const f32x4 r1 = (f32x4){__uint_as_float(w_.z << 16), __uint_as_float(w_.z & 0xffff0000u), __uint_as_float(w_.w << 16), __uint_as_float(w_.w & 0xffff0000u)};
;                     const f32x4 v0 = acc[ai][bj][m][0] + r0, v1 = acc[ai][bj][m][1] + r1;
;                     if (out32) { *(f32x4*)(out32 + off + bj * HALF) = v0; *(f32x4*)(out32 + off + bj * HALF + 4) = v1; }
.LBB0_355:
	s_waitcnt lgkmcnt(0)
	v_lshlrev_b64 v[34:35], 10, v[216:217]
	v_lshl_add_u64 v[34:35], v[34:35], 0, v[212:213]
	v_lshlrev_b32_e32 v36, 16, v142
	v_and_b32_e32 v37, 0xffff0000, v142
	v_lshlrev_b32_e32 v38, 16, v143
	v_and_b32_e32 v39, 0xffff0000, v143
	v_lshlrev_b32_e32 v40, 16, v144
	v_and_b32_e32 v41, 0xffff0000, v144
	v_lshlrev_b32_e32 v42, 16, v145
	v_and_b32_e32 v43, 0xffff0000, v145
	v_pk_add_f32 v[32:33], v[32:33], v[38:39]
	v_pk_add_f32 v[30:31], v[30:31], v[36:37]
	v_pk_add_f32 v[28:29], v[28:29], v[42:43]
	v_pk_add_f32 v[26:27], v[26:27], v[40:41]
	s_and_b64 vcc, exec, s[46:47]
	v_lshl_add_u64 v[36:37], v[34:35], 2, s[10:11]
	v_lshl_add_u64 v[36:37], v[36:37], 0, v[200:201]
	s_cbranch_vccnz .LBB0_357
	s_nop 1
	v_permlane32_swap_b32_e32 v30, v26
	v_permlane32_swap_b32_e32 v31, v27
	v_permlane32_swap_b32_e32 v32, v28
	v_permlane32_swap_b32_e32 v33, v29
	global_store_dwordx4 v[36:37], v[30:33], off
	global_store_dwordx4 v[36:37], v[26:29], off offset:64

;     __device__ __forceinline__ void operator()(const f32x4 (&acc)[2][2][4][2], const Unit& u, int wr, int wc, int fr, int fq, PG8_LAS unsigned char* lds, int& rs_pm, int& rs_tog) const {
;     ...
;                     const u32x4 w_ = pre[slot][mm][bj];
;                     const f32x4 r0 = (f32x4){__uint_as_float(w_.x << 16), __uint_as_float(w_.x & 0xffff0000u), __uint_as_float(w_.y << 16), __uint_as_float(w_.y & 0xffff0000u)};
;                     const f32x4 r1 = (f32x4){__uint_as_float(w_.z << 16), __uint_as_float(w_.z & 0xffff0000u), __uint_as_float(w_.w << 16), __uint_as_float(w_.w & 0xffff0000u)};
;                     const f32x4 v0 = acc[ai][bj][m][0] + r0, v1 = acc[ai][bj][m][1] + r1;
;                     if (out32) { *(f32x4*)(out32 + off + bj * HALF) = v0; *(f32x4*)(out32 + off + bj * HALF + 4) = v1; }
.LBB0_360:
	v_lshlrev_b32_e32 v28, 16, v138
	v_and_b32_e32 v29, 0xffff0000, v138
	v_lshlrev_b32_e32 v30, 16, v139
	v_and_b32_e32 v31, 0xffff0000, v139
	v_lshlrev_b32_e32 v32, 16, v140
	v_and_b32_e32 v33, 0xffff0000, v140
	v_lshlrev_b32_e32 v38, 16, v141
	v_and_b32_e32 v39, 0xffff0000, v141
	v_pk_add_f32 v[24:25], v[24:25], v[30:31]
	v_pk_add_f32 v[22:23], v[22:23], v[28:29]
	v_pk_add_f32 v[20:21], v[20:21], v[38:39]
	s_and_b64 vcc, exec, s[46:47]
	v_pk_add_f32 v[18:19], v[18:19], v[32:33]
	s_cbranch_vccnz .LBB0_362
	s_nop 1
	v_permlane32_swap_b32_e32 v22, v18
	v_permlane32_swap_b32_e32 v23, v19
	v_permlane32_swap_b32_e32 v24, v20
	v_permlane32_swap_b32_e32 v25, v21
	global_store_dwordx4 v[36:37], v[22:25], off offset:512
	global_store_dwordx4 v[36:37], v[18:21], off offset:576

;     __device__ __forceinline__ void operator()(const f32x4 (&acc)[2][2][4][2], const Unit& u, int wr, int wc, int fr, int fq, PG8_LAS unsigned char* lds, int& rs_pm, int& rs_tog) const {
;     ...
;                     const u32x4 w_ = pre[slot][mm][bj];
;                     const f32x4 r0 = (f32x4){__uint_as_float(w_.x << 16), __uint_as_float(w_.x & 0xffff0000u), __uint_as_float(w_.y << 16), __uint_as_float(w_.y & 0xffff0000u)};
;                     const f32x4 r1 = (f32x4){__uint_as_float(w_.z << 16), __uint_as_float(w_.z & 0xffff0000u), __uint_as_float(w_.w << 16), __uint_as_float(w_.w & 0xffff0000u)};
;                     const f32x4 v0 = acc[ai][bj][m][0] + r0, v1 = acc[ai][bj][m][1] + r1;
;                     if (out32) { *(f32x4*)(out32 + off + bj * HALF) = v0; *(f32x4*)(out32 + off + bj * HALF + 4) = v1; }
.LBB0_368:
	s_waitcnt lgkmcnt(0)
	v_lshlrev_b64 v[18:19], 10, v[214:215]
	v_lshl_add_u64 v[18:19], v[18:19], 0, v[212:213]
	v_lshlrev_b32_e32 v20, 16, v118
	v_and_b32_e32 v21, 0xffff0000, v118
	v_lshlrev_b32_e32 v22, 16, v119
	v_and_b32_e32 v23, 0xffff0000, v119
	v_lshlrev_b32_e32 v24, 16, v120
	v_and_b32_e32 v25, 0xffff0000, v120
	v_lshlrev_b32_e32 v26, 16, v121
	v_and_b32_e32 v27, 0xffff0000, v121
	v_pk_add_f32 v[16:17], v[16:17], v[22:23]
	v_pk_add_f32 v[14:15], v[14:15], v[20:21]
	v_pk_add_f32 v[12:13], v[12:13], v[26:27]
	v_pk_add_f32 v[10:11], v[10:11], v[24:25]
	s_and_b64 vcc, exec, s[46:47]
	v_lshl_add_u64 v[20:21], v[18:19], 2, s[10:11]
	v_lshl_add_u64 v[20:21], v[20:21], 0, v[200:201]
	s_cbranch_vccnz .LBB0_370
	s_nop 1
	v_permlane32_swap_b32_e32 v14, v10
	v_permlane32_swap_b32_e32 v15, v11
	v_permlane32_swap_b32_e32 v16, v12
	v_permlane32_swap_b32_e32 v17, v13
	global_store_dwordx4 v[20:21], v[14:17], off
	global_store_dwordx4 v[20:21], v[10:13], off offset:64

;     __device__ __forceinline__ void operator()(const f32x4 (&acc)[2][2][4][2], const Unit& u, int wr, int wc, int fr, int fq, PG8_LAS unsigned char* lds, int& rs_pm, int& rs_tog) const {
;     ...
;                     const u32x4 w_ = pre[slot][mm][bj];
;                     const f32x4 r0 = (f32x4){__uint_as_float(w_.x << 16), __uint_as_float(w_.x & 0xffff0000u), __uint_as_float(w_.y << 16), __uint_as_float(w_.y & 0xffff0000u)};
;                     const f32x4 r1 = (f32x4){__uint_as_float(w_.z << 16), __uint_as_float(w_.z & 0xffff0000u), __uint_as_float(w_.w << 16), __uint_as_float(w_.w & 0xffff0000u)};
;                     const f32x4 v0 = acc[ai][bj][m][0] + r0, v1 = acc[ai][bj][m][1] + r1;
;                     if (out32) { *(f32x4*)(out32 + off + bj * HALF) = v0; *(f32x4*)(out32 + off + bj * HALF + 4) = v1; }
.LBB0_373:
	v_lshlrev_b32_e32 v12, 16, v110
	v_and_b32_e32 v13, 0xffff0000, v110
	v_lshlrev_b32_e32 v14, 16, v111
	v_and_b32_e32 v15, 0xffff0000, v111
	v_lshlrev_b32_e32 v16, 16, v112
	v_and_b32_e32 v17, 0xffff0000, v112
	v_lshlrev_b32_e32 v22, 16, v113
	v_and_b32_e32 v23, 0xffff0000, v113
	v_pk_add_f32 v[8:9], v[8:9], v[14:15]
	v_pk_add_f32 v[6:7], v[6:7], v[12:13]
	v_pk_add_f32 v[4:5], v[4:5], v[22:23]
	s_and_b64 vcc, exec, s[46:47]
	v_pk_add_f32 v[2:3], v[2:3], v[16:17]
	s_cbranch_vccnz .LBB0_375
	s_nop 1
	v_permlane32_swap_b32_e32 v6, v2
	v_permlane32_swap_b32_e32 v7, v3
	v_permlane32_swap_b32_e32 v8, v4
	v_permlane32_swap_b32_e32 v9, v5
	global_store_dwordx4 v[20:21], v[6:9], off offset:512
	global_store_dwordx4 v[20:21], v[2:5], off offset:576

;     __host__ __device__ bool next(int i, Unit& u) const {
;         if (rev_n) { i = rev_n - 1 - i; if (i < 0) return false; }
;         const long L = (long)i * G + c; if (L >= nwg) return false;
;         int wgid = (int)L; { const int q = nwg / NXCD, r = nwg % NXCD, xcd = wgid % NXCD, off = wgid / NXCD; wgid = (xcd < r ? xcd * (q + 1) : r * (q + 1) + (xcd - r) * q) + off; }
.LBB0_401:
	s_add_i32 s90, s90, 1
	s_mul_i32 s10, s90, s83
	s_mul_hi_u32 s11, s90, s89
	s_add_i32 s11, s11, s10
	s_mul_i32 s10, s90, s89
	s_add_u32 s10, s10, s2
	s_addc_u32 s11, s11, s3
	v_mov_b64_e32 v[198:199], 0x400
	v_mov_b64_e32 v[200:201], 0x3ff
	v_cmp_gt_i64_e32 vcc, s[10:11], v[200:201]
	s_mov_b32 s91, s20
	v_cmp_lt_i64_e64 s[44:45], s[10:11], v[198:199]
	s_cbranch_vccnz .LBB0_407
	s_ashr_i32 s11, s10, 31
	s_lshr_b32 s11, s11, 29
	s_add_i32 s20, s10, s11
	s_and_b32 s11, s20, -8
	s_sub_i32 s21, s10, s11
	s_cmp_gt_i32 s21, -1
	s_mov_b64 s[10:11], -1
	s_cbranch_scc0 .LBB0_404
	s_lshl_b32 s27, s21, 7
	s_mov_b64 s[10:11], 0
